# loop back-edge rotation (7.11): exit test, tile rotation, mask update and the window loop's row-sum adds moved in front of the closing barrier in the three attention tile loops
# baseline (speedup 1.0000x reference)
.LBB0_1235:
	s_cmp_lt_i32 s99, 0
	s_cselect_b64 s[40:41], -1, 0
	s_cbranch_scc1 .Ldiff_rot_x
	s_add_i32 s50, s54, 1
	s_and_b32 s54, s50, 3
	s_mov_b32 s69, s99
	s_mov_b32 s99, s63
	s_mov_b32 s63, s73
	s_branch .Ldiff_rot_j

.Ldiff_rot_j:
	s_add_u32 s50, s8, -1
	s_addc_u32 s51, s9, -1
	s_andn2_b64 vcc, exec, s[40:41]
	s_and_b64 s[8:9], s[50:51], s[8:9]
	s_waitcnt lgkmcnt(0)
	s_barrier
	s_cbranch_vccz .LBB0_1253

.LBB0_1250:
	s_andn2_b64 vcc, exec, s[40:41]
	s_cbranch_vccnz .LBB0_1235
	s_waitcnt vmcnt(6)
	s_branch .LBB0_1235
.LBB0_1253:
	v_mov_b32_e32 v0, v129
	s_nop 1
	v_permlane32_swap_b32 v0, v129
	v_cndmask_b32_e64 v2, 0, 1, s[38:39]
	v_add_f32_e32 v0, v0, v129
	v_rcp_f32_e32 v0, v0
	v_cmp_ne_u32_e64 s[8:9], 1, v2
	s_andn2_b64 vcc, exec, s[38:39]
	s_mov_b64 s[38:39], -1
	s_cbranch_vccnz .LBB0_1255
	global_load_dwordx4 v[4:7], v[114:115], off offset:48
	global_load_dwordx4 v[8:11], v[114:115], off offset:32
	global_load_dwordx4 v[12:15], v[114:115], off offset:16
	global_load_dwordx4 v[80:83], v[114:115], off
	global_load_dwordx4 v[84:87], v[114:115], off offset:112
	global_load_dwordx4 v[88:91], v[114:115], off offset:96
	global_load_dwordx4 v[92:95], v[114:115], off offset:80
	global_load_dwordx4 v[96:99], v[114:115], off offset:64
	global_load_dwordx4 v[192:195], v[114:115], off offset:176
	global_load_dwordx4 v[196:199], v[114:115], off offset:160
	global_load_dwordx4 v[200:203], v[114:115], off offset:144
	global_load_dwordx4 v[204:207], v[114:115], off offset:128
	global_load_dwordx4 v[208:211], v[114:115], off offset:224
	global_load_dwordx4 v[212:215], v[114:115], off offset:240
	global_load_dwordx4 v[216:219], v[114:115], off offset:208
	global_load_dwordx4 v[220:223], v[114:115], off offset:192
	v_pk_mul_f32 v[2:3], v[30:31], v[0:1] op_sel_hi:[1,0]
	s_waitcnt vmcnt(2)
	v_pk_fma_f32 v[2:3], v[112:113], v[2:3], v[214:215] neg_lo:[1,0,0] neg_hi:[1,0,0]
	s_nop 0
	v_pk_mul_f32 v[214:215], v[2:3], v[2:3]
	v_pk_mul_f32 v[100:101], v[66:67], v[0:1] op_sel_hi:[1,0]
	s_nop 0
	v_pk_fma_f32 v[158:159], v[112:113], v[100:101], v[82:83] neg_lo:[1,0,0] neg_hi:[1,0,0]
	v_pk_mul_f32 v[82:83], v[64:65], v[0:1] op_sel_hi:[1,0]
	v_pk_mul_f32 v[224:225], v[158:159], v[158:159]
	v_pk_fma_f32 v[164:165], v[112:113], v[82:83], v[80:81] neg_lo:[1,0,0] neg_hi:[1,0,0]
	v_pk_mul_f32 v[80:81], v[70:71], v[0:1] op_sel_hi:[1,0]
	v_pk_mul_f32 v[226:227], v[164:165], v[164:165]
	v_pk_fma_f32 v[156:157], v[112:113], v[80:81], v[14:15] neg_lo:[1,0,0] neg_hi:[1,0,0]
	v_pk_mul_f32 v[14:15], v[68:69], v[0:1] op_sel_hi:[1,0]
	v_add_f32_e32 v129, v226, v227
	v_pk_fma_f32 v[166:167], v[112:113], v[14:15], v[12:13] neg_lo:[1,0,0] neg_hi:[1,0,0]
	v_add_f32_e32 v129, v224, v129
	v_pk_mul_f32 v[230:231], v[166:167], v[166:167]
	v_add_f32_e32 v129, v225, v129
	v_pk_mul_f32 v[12:13], v[74:75], v[0:1] op_sel_hi:[1,0]
	v_add_f32_e32 v129, v230, v129
	v_pk_mul_f32 v[228:229], v[156:157], v[156:157]
	v_pk_fma_f32 v[152:153], v[112:113], v[12:13], v[10:11] neg_lo:[1,0,0] neg_hi:[1,0,0]
	v_pk_mul_f32 v[10:11], v[72:73], v[0:1] op_sel_hi:[1,0]
	v_add_f32_e32 v129, v231, v129
	v_pk_fma_f32 v[162:163], v[112:113], v[10:11], v[8:9] neg_lo:[1,0,0] neg_hi:[1,0,0]
	v_add_f32_e32 v129, v228, v129
	v_pk_mul_f32 v[234:235], v[162:163], v[162:163]
	v_add_f32_e32 v129, v229, v129
	v_pk_mul_f32 v[8:9], v[78:79], v[0:1] op_sel_hi:[1,0]
	v_add_f32_e32 v129, v234, v129
	v_pk_mul_f32 v[232:233], v[152:153], v[152:153]
	v_pk_fma_f32 v[110:111], v[112:113], v[8:9], v[6:7] neg_lo:[1,0,0] neg_hi:[1,0,0]
	v_pk_mul_f32 v[6:7], v[76:77], v[0:1] op_sel_hi:[1,0]
	v_add_f32_e32 v129, v235, v129
	v_pk_fma_f32 v[160:161], v[112:113], v[6:7], v[4:5] neg_lo:[1,0,0] neg_hi:[1,0,0]
	v_add_f32_e32 v129, v232, v129
	v_pk_mul_f32 v[238:239], v[160:161], v[160:161]
	v_add_f32_e32 v129, v233, v129
	v_pk_mul_f32 v[4:5], v[50:51], v[0:1] op_sel_hi:[1,0]
	v_add_f32_e32 v129, v238, v129
	v_pk_mul_f32 v[236:237], v[110:111], v[110:111]
	v_pk_fma_f32 v[104:105], v[112:113], v[4:5], v[98:99] neg_lo:[1,0,0] neg_hi:[1,0,0]
	v_pk_mul_f32 v[4:5], v[48:49], v[0:1] op_sel_hi:[1,0]
	v_add_f32_e32 v129, v239, v129
	v_pk_fma_f32 v[154:155], v[112:113], v[4:5], v[96:97] neg_lo:[1,0,0] neg_hi:[1,0,0]
	v_add_f32_e32 v129, v236, v129
	v_pk_mul_f32 v[242:243], v[154:155], v[154:155]
	v_add_f32_e32 v129, v237, v129
	v_pk_mul_f32 v[4:5], v[54:55], v[0:1] op_sel_hi:[1,0]
	v_add_f32_e32 v129, v242, v129
	v_pk_mul_f32 v[240:241], v[104:105], v[104:105]
	v_pk_fma_f32 v[102:103], v[112:113], v[4:5], v[94:95] neg_lo:[1,0,0] neg_hi:[1,0,0]
	v_pk_mul_f32 v[4:5], v[52:53], v[0:1] op_sel_hi:[1,0]
	v_add_f32_e32 v129, v243, v129
	v_pk_fma_f32 v[150:151], v[112:113], v[4:5], v[92:93] neg_lo:[1,0,0] neg_hi:[1,0,0]
	v_add_f32_e32 v129, v240, v129
	v_pk_mul_f32 v[246:247], v[150:151], v[150:151]
	v_add_f32_e32 v129, v241, v129
	v_pk_mul_f32 v[4:5], v[58:59], v[0:1] op_sel_hi:[1,0]
	v_add_f32_e32 v129, v246, v129
	v_pk_mul_f32 v[244:245], v[102:103], v[102:103]
	v_pk_fma_f32 v[98:99], v[112:113], v[4:5], v[90:91] neg_lo:[1,0,0] neg_hi:[1,0,0]
	v_pk_mul_f32 v[4:5], v[56:57], v[0:1] op_sel_hi:[1,0]
	v_add_f32_e32 v129, v247, v129
	v_pk_fma_f32 v[108:109], v[112:113], v[4:5], v[88:89] neg_lo:[1,0,0] neg_hi:[1,0,0]
	v_add_f32_e32 v129, v244, v129
	v_pk_mul_f32 v[250:251], v[108:109], v[108:109]
	v_add_f32_e32 v129, v245, v129
	v_pk_mul_f32 v[4:5], v[62:63], v[0:1] op_sel_hi:[1,0]
	v_add_f32_e32 v129, v250, v129
	v_pk_mul_f32 v[248:249], v[98:99], v[98:99]
	v_pk_fma_f32 v[94:95], v[112:113], v[4:5], v[86:87] neg_lo:[1,0,0] neg_hi:[1,0,0]
	v_pk_mul_f32 v[4:5], v[60:61], v[0:1] op_sel_hi:[1,0]
	v_add_f32_e32 v129, v251, v129
	v_pk_fma_f32 v[106:107], v[112:113], v[4:5], v[84:85] neg_lo:[1,0,0] neg_hi:[1,0,0]
	v_add_f32_e32 v129, v248, v129
	v_pk_mul_f32 v[178:179], v[106:107], v[106:107]
	v_add_f32_e32 v129, v249, v129
	v_pk_mul_f32 v[4:5], v[34:35], v[0:1] op_sel_hi:[1,0]
	v_add_f32_e32 v129, v178, v129
	v_pk_mul_f32 v[252:253], v[94:95], v[94:95]
	v_pk_fma_f32 v[88:89], v[112:113], v[4:5], v[206:207] neg_lo:[1,0,0] neg_hi:[1,0,0]
	v_pk_mul_f32 v[4:5], v[32:33], v[0:1] op_sel_hi:[1,0]
	v_add_f32_e32 v129, v179, v129
	v_pk_fma_f32 v[100:101], v[112:113], v[4:5], v[204:205] neg_lo:[1,0,0] neg_hi:[1,0,0]
	v_add_f32_e32 v129, v252, v129
	v_pk_mul_f32 v[204:205], v[100:101], v[100:101]
	v_add_f32_e32 v129, v253, v129
	v_pk_mul_f32 v[4:5], v[38:39], v[0:1] op_sel_hi:[1,0]
	v_add_f32_e32 v129, v204, v129
	v_pk_mul_f32 v[206:207], v[88:89], v[88:89]
	v_pk_fma_f32 v[86:87], v[112:113], v[4:5], v[202:203] neg_lo:[1,0,0] neg_hi:[1,0,0]
	v_pk_mul_f32 v[4:5], v[36:37], v[0:1] op_sel_hi:[1,0]
	v_add_f32_e32 v129, v205, v129
	v_pk_fma_f32 v[96:97], v[112:113], v[4:5], v[200:201] neg_lo:[1,0,0] neg_hi:[1,0,0]
	v_add_f32_e32 v129, v206, v129
	v_pk_mul_f32 v[200:201], v[96:97], v[96:97]
	v_add_f32_e32 v129, v207, v129
	v_pk_mul_f32 v[4:5], v[42:43], v[0:1] op_sel_hi:[1,0]
	v_add_f32_e32 v129, v200, v129
	v_pk_mul_f32 v[202:203], v[86:87], v[86:87]
	v_pk_fma_f32 v[82:83], v[112:113], v[4:5], v[198:199] neg_lo:[1,0,0] neg_hi:[1,0,0]
	v_pk_mul_f32 v[4:5], v[40:41], v[0:1] op_sel_hi:[1,0]
	v_add_f32_e32 v129, v201, v129
	v_pk_fma_f32 v[92:93], v[112:113], v[4:5], v[196:197] neg_lo:[1,0,0] neg_hi:[1,0,0]
	v_add_f32_e32 v129, v202, v129
	v_pk_mul_f32 v[196:197], v[92:93], v[92:93]
	v_add_f32_e32 v129, v203, v129
	v_pk_mul_f32 v[4:5], v[46:47], v[0:1] op_sel_hi:[1,0]
	v_add_f32_e32 v129, v196, v129
	v_pk_mul_f32 v[198:199], v[82:83], v[82:83]
	v_pk_fma_f32 v[14:15], v[112:113], v[4:5], v[194:195] neg_lo:[1,0,0] neg_hi:[1,0,0]
	v_pk_mul_f32 v[4:5], v[44:45], v[0:1] op_sel_hi:[1,0]
	v_add_f32_e32 v129, v197, v129
	v_pk_fma_f32 v[90:91], v[112:113], v[4:5], v[192:193] neg_lo:[1,0,0] neg_hi:[1,0,0]
	v_add_f32_e32 v129, v198, v129
	v_pk_mul_f32 v[192:193], v[90:91], v[90:91]
	v_add_f32_e32 v129, v199, v129
	v_pk_mul_f32 v[4:5], v[18:19], v[0:1] op_sel_hi:[1,0]
	v_add_f32_e32 v129, v192, v129
	v_pk_mul_f32 v[194:195], v[14:15], v[14:15]
	s_waitcnt vmcnt(0)
	v_pk_fma_f32 v[10:11], v[112:113], v[4:5], v[222:223] neg_lo:[1,0,0] neg_hi:[1,0,0]
	v_pk_mul_f32 v[4:5], v[16:17], v[0:1] op_sel_hi:[1,0]
	v_add_f32_e32 v129, v193, v129
	v_pk_fma_f32 v[84:85], v[112:113], v[4:5], v[220:221] neg_lo:[1,0,0] neg_hi:[1,0,0]
	v_add_f32_e32 v129, v194, v129
	v_pk_mul_f32 v[220:221], v[84:85], v[84:85]
	v_add_f32_e32 v129, v195, v129
	v_pk_mul_f32 v[4:5], v[22:23], v[0:1] op_sel_hi:[1,0]
	v_add_f32_e32 v129, v220, v129
	v_pk_mul_f32 v[222:223], v[10:11], v[10:11]
	v_pk_fma_f32 v[8:9], v[112:113], v[4:5], v[218:219] neg_lo:[1,0,0] neg_hi:[1,0,0]
	v_pk_mul_f32 v[4:5], v[20:21], v[0:1] op_sel_hi:[1,0]
	v_add_f32_e32 v129, v221, v129
	v_pk_fma_f32 v[80:81], v[112:113], v[4:5], v[216:217] neg_lo:[1,0,0] neg_hi:[1,0,0]
	v_add_f32_e32 v129, v222, v129
	v_pk_mul_f32 v[216:217], v[80:81], v[80:81]
	v_add_f32_e32 v129, v223, v129
	v_pk_mul_f32 v[4:5], v[26:27], v[0:1] op_sel_hi:[1,0]
	v_add_f32_e32 v129, v216, v129
	v_pk_mul_f32 v[218:219], v[8:9], v[8:9]
	v_pk_fma_f32 v[6:7], v[112:113], v[4:5], v[210:211] neg_lo:[1,0,0] neg_hi:[1,0,0]
	v_pk_mul_f32 v[4:5], v[24:25], v[0:1] op_sel_hi:[1,0]
	v_add_f32_e32 v129, v217, v129
	v_pk_fma_f32 v[12:13], v[112:113], v[4:5], v[208:209] neg_lo:[1,0,0] neg_hi:[1,0,0]
	v_add_f32_e32 v129, v218, v129
	v_pk_mul_f32 v[208:209], v[12:13], v[12:13]
	v_add_f32_e32 v129, v219, v129
	v_add_f32_e32 v129, v208, v129
	v_pk_mul_f32 v[210:211], v[6:7], v[6:7]
	v_pk_mul_f32 v[4:5], v[28:29], v[0:1] op_sel_hi:[1,0]
	v_add_f32_e32 v129, v209, v129
	v_pk_fma_f32 v[4:5], v[112:113], v[4:5], v[212:213] neg_lo:[1,0,0] neg_hi:[1,0,0]
	v_add_f32_e32 v129, v210, v129
	v_pk_mul_f32 v[212:213], v[4:5], v[4:5]
	v_add_f32_e32 v129, v211, v129
	v_add_f32_e32 v129, v212, v129
	v_add_f32_e32 v129, v213, v129
	v_add_f32_e32 v129, v214, v129
	v_add_f32_e32 v129, v215, v129
	v_mov_b32_e32 v178, v129
	s_nop 1
	v_permlane32_swap_b32 v129, v178
	global_load_dwordx4 v[192:195], v[124:125], off
	v_add_f32_e32 v129, v129, v178
	v_fmamk_f32 v129, v129, 0x3c000000, v177
	v_mul_f32_e32 v178, 0x4b800000, v129
	v_cmp_gt_f32_e32 vcc, s52, v129
	s_nop 1
	v_cndmask_b32_e32 v129, v129, v178, vcc
	v_rsq_f32_e32 v129, v129
	s_nop 0
	v_mul_f32_e32 v178, 0x45800000, v129
	v_cndmask_b32_e32 v129, v129, v178, vcc
	v_mul_f32_e32 v178, v189, v129
	v_pk_mul_f32 v[164:165], v[164:165], v[178:179] op_sel_hi:[1,0]
	v_pk_mul_f32 v[158:159], v[158:159], v[178:179] op_sel_hi:[1,0]
	v_pk_mul_f32 v[156:157], v[156:157], v[178:179] op_sel_hi:[1,0]
	v_pk_mul_f32 v[162:163], v[162:163], v[178:179] op_sel_hi:[1,0]
	v_pk_mul_f32 v[152:153], v[152:153], v[178:179] op_sel_hi:[1,0]
	v_pk_mul_f32 v[110:111], v[110:111], v[178:179] op_sel_hi:[1,0]
	s_waitcnt vmcnt(0)
	v_pk_mul_f32 v[164:165], v[192:193], v[164:165]
	v_pk_mul_f32 v[158:159], v[194:195], v[158:159]
	v_cvt_pk_bf16_f32 v164, v164, v165
	v_cvt_pk_bf16_f32 v165, v158, v159
	global_store_dwordx2 v[144:145], v[164:165], off
	global_load_dwordx4 v[192:195], v[124:125], off offset:32
	v_pk_mul_f32 v[158:159], v[166:167], v[178:179] op_sel_hi:[1,0]
	s_waitcnt vmcnt(0)
	v_pk_mul_f32 v[156:157], v[194:195], v[156:157]
	v_pk_mul_f32 v[158:159], v[192:193], v[158:159]
	s_nop 0
	v_cvt_pk_bf16_f32 v158, v158, v159
	v_cvt_pk_bf16_f32 v159, v156, v157
	global_store_dwordx2 v[144:145], v[158:159], off offset:16
	global_load_dwordx4 v[156:159], v[124:125], off offset:64
	s_waitcnt vmcnt(0)
	v_pk_mul_f32 v[156:157], v[156:157], v[162:163]
	v_pk_mul_f32 v[152:153], v[158:159], v[152:153]
	v_cvt_pk_bf16_f32 v156, v156, v157
	v_cvt_pk_bf16_f32 v157, v152, v153
	global_store_dwordx2 v[144:145], v[156:157], off offset:32
	global_load_dwordx4 v[156:159], v[124:125], off offset:96
	v_pk_mul_f32 v[152:153], v[160:161], v[178:179] op_sel_hi:[1,0]
	s_waitcnt vmcnt(0)
	v_pk_mul_f32 v[110:111], v[158:159], v[110:111]
	v_pk_mul_f32 v[152:153], v[156:157], v[152:153]
	s_nop 0
	v_cvt_pk_bf16_f32 v152, v152, v153
	v_cvt_pk_bf16_f32 v153, v110, v111
	global_store_dwordx2 v[144:145], v[152:153], off offset:48
	global_load_dwordx4 v[156:159], v[124:125], off offset:128
	v_pk_mul_f32 v[110:111], v[154:155], v[178:179] op_sel_hi:[1,0]
	v_pk_mul_f32 v[104:105], v[104:105], v[178:179] op_sel_hi:[1,0]
	v_pk_mul_f32 v[102:103], v[102:103], v[178:179] op_sel_hi:[1,0]
	v_pk_mul_f32 v[108:109], v[108:109], v[178:179] op_sel_hi:[1,0]
	v_pk_mul_f32 v[98:99], v[98:99], v[178:179] op_sel_hi:[1,0]
	v_pk_mul_f32 v[94:95], v[94:95], v[178:179] op_sel_hi:[1,0]
	s_waitcnt vmcnt(0)
	v_pk_mul_f32 v[110:111], v[156:157], v[110:111]
	v_pk_mul_f32 v[104:105], v[158:159], v[104:105]
	v_cvt_pk_bf16_f32 v110, v110, v111
	v_cvt_pk_bf16_f32 v111, v104, v105
	global_store_dwordx2 v[144:145], v[110:111], off offset:64
	global_load_dwordx4 v[152:155], v[124:125], off offset:160
	v_pk_mul_f32 v[104:105], v[150:151], v[178:179] op_sel_hi:[1,0]
	s_waitcnt vmcnt(0)
	v_pk_mul_f32 v[102:103], v[102:103], v[154:155]
	v_pk_mul_f32 v[104:105], v[104:105], v[152:153]
	s_nop 0
	v_cvt_pk_bf16_f32 v104, v104, v105
	v_cvt_pk_bf16_f32 v105, v102, v103
	global_store_dwordx2 v[144:145], v[104:105], off offset:80
	global_load_dwordx4 v[102:105], v[124:125], off offset:192
	s_waitcnt vmcnt(0)
	v_pk_mul_f32 v[102:103], v[108:109], v[102:103]
	v_pk_mul_f32 v[98:99], v[98:99], v[104:105]
	v_cvt_pk_bf16_f32 v102, v102, v103
	v_cvt_pk_bf16_f32 v103, v98, v99
	global_store_dwordx2 v[144:145], v[102:103], off offset:96
	global_load_dwordx4 v[102:105], v[124:125], off offset:224
	v_pk_mul_f32 v[98:99], v[106:107], v[178:179] op_sel_hi:[1,0]
	s_waitcnt vmcnt(0)
	v_pk_mul_f32 v[94:95], v[94:95], v[104:105]
	v_pk_mul_f32 v[98:99], v[98:99], v[102:103]
	s_nop 0
	v_cvt_pk_bf16_f32 v98, v98, v99
	v_cvt_pk_bf16_f32 v99, v94, v95
	global_store_dwordx2 v[144:145], v[98:99], off offset:112
	global_load_dwordx4 v[102:105], v[124:125], off offset:256
	v_pk_mul_f32 v[94:95], v[100:101], v[178:179] op_sel_hi:[1,0]
	v_pk_mul_f32 v[88:89], v[88:89], v[178:179] op_sel_hi:[1,0]
	v_pk_mul_f32 v[86:87], v[86:87], v[178:179] op_sel_hi:[1,0]
	v_pk_mul_f32 v[92:93], v[92:93], v[178:179] op_sel_hi:[1,0]
	v_pk_mul_f32 v[82:83], v[82:83], v[178:179] op_sel_hi:[1,0]
	v_pk_mul_f32 v[14:15], v[14:15], v[178:179] op_sel_hi:[1,0]
	s_waitcnt vmcnt(0)
	v_pk_mul_f32 v[94:95], v[94:95], v[102:103]
	v_pk_mul_f32 v[88:89], v[88:89], v[104:105]
	v_cvt_pk_bf16_f32 v94, v94, v95
	v_cvt_pk_bf16_f32 v95, v88, v89
	global_store_dwordx2 v[144:145], v[94:95], off offset:128
	global_load_dwordx4 v[98:101], v[124:125], off offset:288
	v_pk_mul_f32 v[88:89], v[96:97], v[178:179] op_sel_hi:[1,0]
	s_waitcnt vmcnt(0)
	v_pk_mul_f32 v[86:87], v[86:87], v[100:101]
	v_pk_mul_f32 v[88:89], v[88:89], v[98:99]
	s_nop 0
	v_cvt_pk_bf16_f32 v88, v88, v89
	v_cvt_pk_bf16_f32 v89, v86, v87
	global_store_dwordx2 v[144:145], v[88:89], off offset:144
	global_load_dwordx4 v[86:89], v[124:125], off offset:320
	s_waitcnt vmcnt(0)
	v_pk_mul_f32 v[86:87], v[92:93], v[86:87]
	v_pk_mul_f32 v[82:83], v[82:83], v[88:89]
	v_cvt_pk_bf16_f32 v86, v86, v87
	v_cvt_pk_bf16_f32 v87, v82, v83
	global_store_dwordx2 v[144:145], v[86:87], off offset:160
	global_load_dwordx4 v[86:89], v[124:125], off offset:352
	v_pk_mul_f32 v[82:83], v[90:91], v[178:179] op_sel_hi:[1,0]
	s_waitcnt vmcnt(0)
	v_pk_mul_f32 v[14:15], v[14:15], v[88:89]
	v_pk_mul_f32 v[82:83], v[82:83], v[86:87]
	s_nop 0
	v_cvt_pk_bf16_f32 v82, v82, v83
	v_cvt_pk_bf16_f32 v83, v14, v15
	global_store_dwordx2 v[144:145], v[82:83], off offset:176
	global_load_dwordx4 v[86:89], v[124:125], off offset:384
	v_pk_mul_f32 v[14:15], v[84:85], v[178:179] op_sel_hi:[1,0]
	v_pk_mul_f32 v[10:11], v[10:11], v[178:179] op_sel_hi:[1,0]
	v_pk_mul_f32 v[8:9], v[8:9], v[178:179] op_sel_hi:[1,0]
	v_pk_mul_f32 v[12:13], v[12:13], v[178:179] op_sel_hi:[1,0]
	v_pk_mul_f32 v[6:7], v[6:7], v[178:179] op_sel_hi:[1,0]
	v_pk_mul_f32 v[4:5], v[4:5], v[178:179] op_sel_hi:[1,0]
	v_pk_mul_f32 v[2:3], v[2:3], v[178:179] op_sel_hi:[1,0]
	s_waitcnt vmcnt(0)
	v_pk_mul_f32 v[14:15], v[14:15], v[86:87]
	v_pk_mul_f32 v[10:11], v[10:11], v[88:89]
	v_cvt_pk_bf16_f32 v14, v14, v15
	v_cvt_pk_bf16_f32 v15, v10, v11
	global_store_dwordx2 v[144:145], v[14:15], off offset:192
	global_load_dwordx4 v[82:85], v[124:125], off offset:416
	v_pk_mul_f32 v[10:11], v[80:81], v[178:179] op_sel_hi:[1,0]
	s_waitcnt vmcnt(0)
	v_pk_mul_f32 v[8:9], v[8:9], v[84:85]
	v_pk_mul_f32 v[10:11], v[10:11], v[82:83]
	s_nop 0
	v_cvt_pk_bf16_f32 v10, v10, v11
	v_cvt_pk_bf16_f32 v11, v8, v9
	global_store_dwordx2 v[144:145], v[10:11], off offset:208
	global_load_dwordx4 v[8:11], v[124:125], off offset:448
	s_waitcnt vmcnt(0)
	v_pk_mul_f32 v[8:9], v[12:13], v[8:9]
	v_pk_mul_f32 v[6:7], v[6:7], v[10:11]
	v_cvt_pk_bf16_f32 v8, v8, v9
	v_cvt_pk_bf16_f32 v9, v6, v7
	global_store_dwordx2 v[144:145], v[8:9], off offset:224
	global_load_dwordx4 v[6:9], v[124:125], off offset:480
	s_waitcnt vmcnt(0)
	v_pk_mul_f32 v[4:5], v[4:5], v[6:7]
	v_pk_mul_f32 v[2:3], v[2:3], v[8:9]
	v_cvt_pk_bf16_f32 v4, v4, v5
	v_cvt_pk_bf16_f32 v5, v2, v3
	global_store_dwordx2 v[144:145], v[4:5], off offset:240
	s_cbranch_execnz .LBB0_1219
	s_branch .LBB0_1256

.LBB0_1340:
	s_cmp_lt_i32 s7, 0
	s_cselect_b64 s[12:13], -1, 0
	s_cbranch_scc1 .Lslc_rot_j
	s_add_i32 s6, s14, 1
	s_and_b32 s14, s6, 3
	s_mov_b32 s6, s7
	s_mov_b32 s7, s18
	s_mov_b32 s18, s15
.Lslc_rot_j:
	s_add_u32 s16, s10, -1
	s_addc_u32 s17, s11, -1
	v_mov_b32_e32 v191, v123
	s_andn2_b64 vcc, exec, s[12:13]
	s_and_b64 s[10:11], s[16:17], s[10:11]
	s_waitcnt lgkmcnt(0)
	s_barrier
	s_cbranch_vccz .LBB0_1345
	s_branch .LBB0_1328

.Lwin_cont:
	v_add3_u32 v163, s7, v200, v201
	v_add3_u32 v163, v163, v202, v203
	v_sub_f32_e32 v98, v98, v162
	v_sub_f32_e32 v99, v99, v162
	v_sub_f32_e32 v100, v100, v162
	v_sub_f32_e32 v101, v101, v162
	v_sub_f32_e32 v102, v102, v162
	v_sub_f32_e32 v103, v103, v162
	v_sub_f32_e32 v104, v104, v162
	v_sub_f32_e32 v105, v105, v162
	v_add_u32_e32 v178, v163, v204
	v_exp_f32_e32 v98, v98
	v_exp_f32_e32 v99, v99
	v_exp_f32_e32 v100, v100
	v_exp_f32_e32 v101, v101
	v_exp_f32_e32 v102, v102
	v_exp_f32_e32 v103, v103
	v_exp_f32_e32 v104, v104
	v_exp_f32_e32 v105, v105
	ds_read_b64_tr_b16 v[172:173], v178 offset:8192
	ds_read_b64_tr_b16 v[174:175], v178 offset:9216
	v_add_u32_e32 v163, v163, v205
	ds_read_b64_tr_b16 v[212:213], v163 offset:8192
	ds_read_b64_tr_b16 v[214:215], v163 offset:9216
	ds_read_b64_tr_b16 v[216:217], v178 offset:10240
	ds_read_b64_tr_b16 v[218:219], v178 offset:11264
	v_cvt_pk_bf16_f32 v164, v98, v99
	v_cvt_pk_bf16_f32 v165, v100, v101
	v_cvt_pk_bf16_f32 v166, v102, v103
	v_cvt_pk_bf16_f32 v167, v104, v105
	v_sub_f32_e32 v114, v114, v162
	v_sub_f32_e32 v115, v115, v162
	s_waitcnt lgkmcnt(4)
	v_mfma_f32_32x32x16_bf16 v[82:97], v[172:175], v[164:167], v[82:97]
	v_sub_f32_e32 v116, v116, v162
	v_sub_f32_e32 v117, v117, v162
	v_sub_f32_e32 v118, v118, v162
	v_sub_f32_e32 v119, v119, v162
	v_sub_f32_e32 v120, v120, v162
	v_sub_f32_e32 v121, v121, v162
	v_sub_f32_e32 v106, v106, v162
	s_waitcnt lgkmcnt(2)
	v_mfma_f32_32x32x16_bf16 v[66:81], v[212:215], v[164:167], v[66:81]
	v_sub_f32_e32 v122, v122, v162
	v_sub_f32_e32 v107, v107, v162
	v_sub_f32_e32 v123, v123, v162
	v_sub_f32_e32 v108, v108, v162
	v_sub_f32_e32 v124, v124, v162
	v_sub_f32_e32 v109, v109, v162
	v_sub_f32_e32 v125, v125, v162
	v_sub_f32_e32 v110, v110, v162
	v_sub_f32_e32 v126, v126, v162
	v_sub_f32_e32 v111, v111, v162
	v_sub_f32_e32 v127, v127, v162
	v_sub_f32_e32 v112, v112, v162
	v_sub_f32_e32 v128, v128, v162
	v_sub_f32_e32 v113, v113, v162
	v_sub_f32_e32 v129, v129, v162
	ds_read_b64_tr_b16 v[220:221], v163 offset:10240
	ds_read_b64_tr_b16 v[222:223], v163 offset:11264
	v_exp_f32_e32 v114, v114
	v_exp_f32_e32 v115, v115
	v_exp_f32_e32 v116, v116
	v_exp_f32_e32 v117, v117
	v_exp_f32_e32 v118, v118
	v_exp_f32_e32 v119, v119
	v_exp_f32_e32 v120, v120
	v_exp_f32_e32 v121, v121
	v_exp_f32_e32 v106, v106
	v_exp_f32_e32 v122, v122
	v_exp_f32_e32 v107, v107
	v_exp_f32_e32 v123, v123
	v_exp_f32_e32 v108, v108
	v_exp_f32_e32 v124, v124
	v_exp_f32_e32 v109, v109
	v_exp_f32_e32 v125, v125
	v_exp_f32_e32 v110, v110
	v_exp_f32_e32 v126, v126
	v_exp_f32_e32 v111, v111
	v_exp_f32_e32 v127, v127
	v_exp_f32_e32 v112, v112
	v_exp_f32_e32 v128, v128
	v_exp_f32_e32 v113, v113
	v_exp_f32_e32 v129, v129
	v_cvt_pk_bf16_f32 v168, v106, v107
	v_cvt_pk_bf16_f32 v169, v108, v109
	v_cvt_pk_bf16_f32 v170, v110, v111
	v_cvt_pk_bf16_f32 v171, v112, v113
	v_cvt_pk_bf16_f32 v208, v114, v115
	v_cvt_pk_bf16_f32 v209, v116, v117
	v_cvt_pk_bf16_f32 v210, v118, v119
	v_cvt_pk_bf16_f32 v211, v120, v121
	v_cvt_pk_bf16_f32 v172, v122, v123
	v_cvt_pk_bf16_f32 v173, v124, v125
	v_cvt_pk_bf16_f32 v174, v126, v127
	v_cvt_pk_bf16_f32 v175, v128, v129
	s_waitcnt lgkmcnt(2)
	v_mfma_f32_32x32x16_bf16 v[82:97], v[216:219], v[168:171], v[82:97]
	ds_read_b64_tr_b16 v[164:165], v178 offset:12288
	ds_read_b64_tr_b16 v[166:167], v178 offset:13312
	ds_read_b64_tr_b16 v[212:213], v163 offset:12288
	ds_read_b64_tr_b16 v[214:215], v163 offset:13312
	s_waitcnt lgkmcnt(4)
	v_mfma_f32_32x32x16_bf16 v[66:81], v[220:223], v[168:171], v[66:81]
	s_waitcnt lgkmcnt(2)
	v_mfma_f32_32x32x16_bf16 v[82:97], v[164:167], v[208:211], v[82:97]
	ds_read_b64_tr_b16 v[164:165], v178 offset:14336
	ds_read_b64_tr_b16 v[166:167], v178 offset:15360
	ds_read_b64_tr_b16 v[168:169], v163 offset:14336
	ds_read_b64_tr_b16 v[170:171], v163 offset:15360
	s_waitcnt lgkmcnt(4)
	v_mfma_f32_32x32x16_bf16 v[66:81], v[212:215], v[208:211], v[66:81]
	s_waitcnt lgkmcnt(2)
	v_mfma_f32_32x32x16_bf16 v[82:97], v[164:167], v[172:175], v[82:97]
	s_waitcnt lgkmcnt(0)
	v_mfma_f32_32x32x16_bf16 v[66:81], v[168:171], v[172:175], v[66:81]
	v_add_f32_e32 v98, v98, v114
	v_add_f32_e32 v98, 0, v98
	v_add_f32_e32 v99, v99, v115
	v_add_f32_e32 v98, v99, v98
	v_add_f32_e32 v99, v100, v116
	v_add_f32_e32 v98, v99, v98
	v_add_f32_e32 v99, v101, v117
	v_add_f32_e32 v98, v99, v98
	v_add_f32_e32 v99, v102, v118
	v_add_f32_e32 v98, v99, v98
	v_add_f32_e32 v99, v103, v119
	v_add_f32_e32 v98, v99, v98
	v_add_f32_e32 v99, v104, v120
	v_add_f32_e32 v98, v99, v98
	v_add_f32_e32 v99, v105, v121
	v_add_f32_e32 v98, v99, v98
	v_add_f32_e32 v99, v106, v122
	v_add_f32_e32 v98, v99, v98
	v_add_f32_e32 v99, v107, v123
	v_add_f32_e32 v98, v99, v98
	v_add_f32_e32 v99, v108, v124
	v_add_f32_e32 v98, v99, v98
	v_add_f32_e32 v99, v109, v125
	v_add_f32_e32 v98, v99, v98
	v_add_f32_e32 v99, v110, v126
	v_add_f32_e32 v98, v99, v98
	v_add_f32_e32 v99, v111, v127
	v_add_f32_e32 v98, v99, v98
	v_add_f32_e32 v99, v112, v128
	v_add_f32_e32 v98, v99, v98
	v_add_f32_e32 v99, v113, v129
	v_add_f32_e32 v98, v99, v98
	v_fmac_f32_e32 v98, v206, v0
	s_or_b32 s7, s73, s12
	s_cmp_lt_i32 s7, 0
	s_mov_b64 s[10:11], -1
	s_cbranch_scc0 .LBB0_1368
	s_and_b32 s7, s73, s12
	s_cmp_lt_i32 s7, 0
	s_cbranch_scc0 .LBB0_1365
	s_waitcnt vmcnt(0)
	s_mov_b64 s[10:11], 0

.LBB0_1370:
	s_cmp_lt_i32 s72, 0
	s_cselect_b64 s[10:11], -1, 0
	s_cbranch_scc1 .Lwin_rot_j
	s_add_i32 s6, s6, 1
	s_and_b32 s6, s6, 3
	s_mov_b32 s80, s72
	s_mov_b32 s72, s73
	s_mov_b32 s73, s12
.Lwin_rot_j:
	s_add_u32 s12, s88, -1
	s_addc_u32 s13, s89, -1
	s_andn2_b64 vcc, exec, s[10:11]
	s_and_b64 s[88:89], s[12:13], s[88:89]
	s_waitcnt lgkmcnt(0)
	s_barrier
	s_cbranch_vccz .LBB0_1262
	v_mov_b32_e32 v0, v162
	v_mov_b32_e32 v206, v98
	s_branch .LBB0_1358
